# combination: trimmed load clusters + per-unit wave-group re-sync + scheduler shift + mixer-phase priority for waves 4-7
# baseline (speedup 1.0000x reference)
; #define PG8_STAGE(bufoff, gbase, voff) do { _Pragma("unroll") for (int _i = 0; _i < 2; ++_i) \
;         __builtin_amdgcn_global_load_lds((const unsigned*)((const char*)(gbase) + (voff)[_i]), (LAS unsigned*)(lds + (bufoff) + ldsw + _i * 8192), 16, 0, 0); } while (0)
; #define PG8_LDA(dst, b, h) do { _Pragma("unroll") for (int m = 0; m < 4; ++m) _Pragma("unroll") for (int k = 0; k < 2; ++k) dst[m][k] = *(const LAS bf16x8*)(lds + PG8_SA(b, h) + aoff + m * 2048 + k * 1024); } while (0)
; #define PG8_LDB(dst, b, h) do { _Pragma("unroll") for (int n = 0; n < 2; ++n) _Pragma("unroll") for (int k = 0; k < 2; ++k) dst[n][k] = *(const LAS bf16x8*)(lds + PG8_SB(b, h) + boff + n * 2048 + k * 1024); } while (0)
; #define PG8_MMA(ai, bj, At, Bt) do { __builtin_amdgcn_s_setprio(1); _Pragma("unroll") for (int m = 0; m < 4; ++m) _Pragma("unroll") for (int n = 0; n < 2; ++n) _Pragma("unroll") for (int k = 0; k < 2; ++k) \
;         acc[ai][bj][m][n] = __builtin_amdgcn_mfma_f32_16x16x32_bf16(Bt[n][k], At[m][k], acc[ai][bj][m][n], 0, 0, 0); __builtin_amdgcn_s_setprio(0); } while (0)
; #define PG8_WAIT_V(n) asm volatile("s_waitcnt vmcnt(" #n ")" ::: "memory")
; #define PG8_WAIT_L(n) asm volatile("s_waitcnt lgkmcnt(" #n ")" ::: "memory")
; #define PG8_BAR __builtin_amdgcn_s_barrier()
; template <class Prog>
; __device__ __forceinline__ void gemm_phase(LAS unsigned char* lds, const int K, const Prog& S) {
;     ...
;         for (int t = 0; t < nt; t += 2) {
;             const bool last = (t == nt - 2);
;             const char* a1 = cA + (size_t)(t + 1) * kstep;
;             const char* a2 = last ? nA : cA + (size_t)(t + 2) * kstep; const char* b2 = last ? nB : cB + (size_t)(t + 2) * kstep;
;             const char* a3 = a2 + kstep; const char* b3 = b2 + kstep;
;             PG8_LDB(B0, 0, 0); PG8_SCHED; PG8_LDA(At, 0, 0); PG8_STAGE(PG8_SA(1, 1), a1 + hstep, voffA);
;             PG8_WAIT_L(8); PG8_BAR; PG8_WAIT_L(0); PG8_MMA(0, 0, At, B0); PG8_BAR; PG8_SCHED;
;             PG8_LDB(B1, 0, 1); PG8_STAGE(PG8_SB(0, 0), b2, voffB);
;             PG8_BAR; PG8_WAIT_L(0); PG8_MMA(0, 1, At, B1); PG8_BAR;
;             PG8_LDA(At, 0, 1); PG8_STAGE(PG8_SA(0, 0), a2, voffA);
;             PG8_BAR; PG8_WAIT_L(0); PG8_MMA(1, 0, At, B0); PG8_BAR; PG8_SCHED;
;             PG8_STAGE(PG8_SB(0, 1), b2 + hstep, voffB);
;             PG8_WAIT_V(6); PG8_BAR; PG8_MMA(1, 1, At, B1); PG8_BAR;
.LBB0_101:
	s_add_u32 s44, s40, 0xfff80080
	s_addc_u32 s45, s41, -1
	s_cmp_eq_u32 s69, 28
	s_cselect_b32 s47, s5, s45
	s_cselect_b32 s46, s4, s44
	s_cselect_b32 s45, s13, s15
	s_cselect_b32 s44, s12, s9
	s_add_u32 s76, s40, 0xfff80000
	s_addc_u32 s77, s41, -1
	ds_read_b128 v[128:131], v244
	ds_read_b128 v[132:135], v244 offset:1024
	ds_read_b128 v[136:139], v244 offset:2048
	ds_read_b128 v[140:143], v244 offset:3072
	s_add_i32 m0, s92, 0x8000
	ds_read_b128 v[188:191], v244 offset:16384
	ds_read_b128 v[196:199], v244 offset:17408
	ds_read_b128 v[200:203], v244 offset:18432
	ds_read_b128 v[218:221], v244 offset:19456
	global_load_lds_dwordx4 v184, s[76:77]
	s_add_i32 m0, s92, 0xa000
	ds_read_b128 v[144:147], v216
	ds_read_b128 v[148:151], v216 offset:1024
	ds_read_b128 v[152:155], v216 offset:2048
	ds_read_b128 v[156:159], v216 offset:3072
	global_load_lds_dwordx4 v186, s[76:77]
	s_add_i32 m0, s92, 0xc000
	ds_read_b128 v[160:163], v216 offset:4096
	ds_read_b128 v[164:167], v216 offset:5120
	ds_read_b128 v[168:171], v216 offset:6144
	global_load_lds_dwordx4 v184, s[40:41]
	s_add_i32 m0, s92, 0xe000
	ds_read_b128 v[172:175], v216 offset:7168
	global_load_lds_dwordx4 v186, s[40:41]
	s_waitcnt lgkmcnt(0)
	s_barrier
	v_mfma_f32_16x16x32_bf16 v[124:127], v[128:131], v[144:147], v[124:127]
	v_mfma_f32_16x16x32_bf16 v[116:119], v[136:139], v[144:147], v[116:119]
	v_mfma_f32_16x16x32_bf16 v[108:111], v[128:131], v[152:155], v[108:111]
	v_mfma_f32_16x16x32_bf16 v[100:103], v[136:139], v[152:155], v[100:103]
	v_mfma_f32_16x16x32_bf16 v[92:95], v[128:131], v[160:163], v[92:95]
	v_mfma_f32_16x16x32_bf16 v[84:87], v[136:139], v[160:163], v[84:87]
	v_mfma_f32_16x16x32_bf16 v[76:79], v[128:131], v[168:171], v[76:79]
	v_mfma_f32_16x16x32_bf16 v[68:71], v[136:139], v[168:171], v[68:71]
	v_mfma_f32_16x16x32_bf16 v[124:127], v[132:135], v[148:151], v[124:127]
	v_mfma_f32_16x16x32_bf16 v[116:119], v[140:143], v[148:151], v[116:119]
	v_mfma_f32_16x16x32_bf16 v[108:111], v[132:135], v[156:159], v[108:111]
	v_mfma_f32_16x16x32_bf16 v[100:103], v[140:143], v[156:159], v[100:103]
	v_mfma_f32_16x16x32_bf16 v[92:95], v[132:135], v[164:167], v[92:95]
	v_mfma_f32_16x16x32_bf16 v[84:87], v[140:143], v[164:167], v[84:87]
	v_mfma_f32_16x16x32_bf16 v[76:79], v[132:135], v[172:175], v[76:79]
	v_mfma_f32_16x16x32_bf16 v[68:71], v[140:143], v[172:175], v[68:71]
	v_mfma_f32_16x16x32_bf16 v[120:123], v[188:191], v[144:147], v[120:123]
	v_mfma_f32_16x16x32_bf16 v[112:115], v[200:203], v[144:147], v[112:115]
	v_mfma_f32_16x16x32_bf16 v[104:107], v[188:191], v[152:155], v[104:107]
	v_mfma_f32_16x16x32_bf16 v[96:99], v[200:203], v[152:155], v[96:99]
	v_mfma_f32_16x16x32_bf16 v[88:91], v[188:191], v[160:163], v[88:91]
	v_mfma_f32_16x16x32_bf16 v[80:83], v[200:203], v[160:163], v[80:83]
	v_mfma_f32_16x16x32_bf16 v[72:75], v[188:191], v[168:171], v[72:75]
	v_mfma_f32_16x16x32_bf16 v[64:67], v[200:203], v[168:171], v[64:67]
	v_mfma_f32_16x16x32_bf16 v[120:123], v[196:199], v[148:151], v[120:123]
	v_mfma_f32_16x16x32_bf16 v[112:115], v[218:221], v[148:151], v[112:115]
	v_mfma_f32_16x16x32_bf16 v[104:107], v[196:199], v[156:159], v[104:107]
	v_mfma_f32_16x16x32_bf16 v[96:99], v[218:221], v[156:159], v[96:99]
	v_mfma_f32_16x16x32_bf16 v[88:91], v[196:199], v[164:167], v[88:91]
	v_mfma_f32_16x16x32_bf16 v[80:83], v[218:221], v[164:167], v[80:83]
	v_mfma_f32_16x16x32_bf16 v[72:75], v[196:199], v[172:175], v[72:75]
	v_mfma_f32_16x16x32_bf16 v[64:67], v[218:221], v[172:175], v[64:67]
	s_barrier
	s_add_i32 m0, s92, 0x10000
	ds_read_b128 v[144:147], v216 offset:16384
	ds_read_b128 v[148:151], v216 offset:17408
	global_load_lds_dwordx4 v192, s[44:45]
	s_add_i32 m0, s92, 0x12000
	ds_read_b128 v[152:155], v216 offset:18432
	ds_read_b128 v[156:159], v216 offset:19456
	global_load_lds_dwordx4 v180, s[44:45]
	s_add_i32 m0, s92, 0x14000
	s_add_u32 s76, s44, 0x80000
	s_addc_u32 s77, s45, 0
	ds_read_b128 v[160:163], v216 offset:20480
	ds_read_b128 v[164:167], v216 offset:21504
	global_load_lds_dwordx4 v192, s[76:77]
	s_add_i32 m0, s92, 0x16000
	ds_read_b128 v[168:171], v216 offset:22528
	ds_read_b128 v[172:175], v216 offset:23552
	global_load_lds_dwordx4 v180, s[76:77]
	s_waitcnt vmcnt(4) lgkmcnt(0)
	s_barrier
	v_mfma_f32_16x16x32_bf16 v[60:63], v[128:131], v[144:147], v[60:63]
	v_mfma_f32_16x16x32_bf16 v[52:55], v[136:139], v[144:147], v[52:55]
	v_mfma_f32_16x16x32_bf16 v[44:47], v[128:131], v[152:155], v[44:47]
	v_mfma_f32_16x16x32_bf16 v[36:39], v[136:139], v[152:155], v[36:39]
	v_mfma_f32_16x16x32_bf16 v[28:31], v[128:131], v[160:163], v[28:31]
	v_mfma_f32_16x16x32_bf16 v[20:23], v[136:139], v[160:163], v[20:23]
	v_mfma_f32_16x16x32_bf16 v[12:15], v[128:131], v[168:171], v[12:15]
	v_mfma_f32_16x16x32_bf16 v[4:7], v[136:139], v[168:171], v[4:7]
	v_mfma_f32_16x16x32_bf16 v[60:63], v[132:135], v[148:151], v[60:63]
	v_mfma_f32_16x16x32_bf16 v[52:55], v[140:143], v[148:151], v[52:55]
	v_mfma_f32_16x16x32_bf16 v[44:47], v[132:135], v[156:159], v[44:47]
	v_mfma_f32_16x16x32_bf16 v[36:39], v[140:143], v[156:159], v[36:39]
	v_mfma_f32_16x16x32_bf16 v[28:31], v[132:135], v[164:167], v[28:31]
	v_mfma_f32_16x16x32_bf16 v[20:23], v[140:143], v[164:167], v[20:23]
	v_mfma_f32_16x16x32_bf16 v[12:15], v[132:135], v[172:175], v[12:15]
	v_mfma_f32_16x16x32_bf16 v[4:7], v[140:143], v[172:175], v[4:7]
	v_mfma_f32_16x16x32_bf16 v[56:59], v[188:191], v[144:147], v[56:59]
	v_mfma_f32_16x16x32_bf16 v[48:51], v[200:203], v[144:147], v[48:51]
	v_mfma_f32_16x16x32_bf16 v[40:43], v[188:191], v[152:155], v[40:43]
	v_mfma_f32_16x16x32_bf16 v[32:35], v[200:203], v[152:155], v[32:35]
	v_mfma_f32_16x16x32_bf16 v[24:27], v[188:191], v[160:163], v[24:27]
	v_mfma_f32_16x16x32_bf16 v[16:19], v[200:203], v[160:163], v[16:19]
	v_mfma_f32_16x16x32_bf16 v[8:11], v[188:191], v[168:171], v[8:11]
	v_mfma_f32_16x16x32_bf16 v[0:3], v[200:203], v[168:171], v[0:3]
	v_mfma_f32_16x16x32_bf16 v[56:59], v[196:199], v[148:151], v[56:59]
	v_mfma_f32_16x16x32_bf16 v[48:51], v[218:221], v[148:151], v[48:51]
	v_mfma_f32_16x16x32_bf16 v[40:43], v[196:199], v[156:159], v[40:43]
	v_mfma_f32_16x16x32_bf16 v[32:35], v[218:221], v[156:159], v[32:35]
	v_mfma_f32_16x16x32_bf16 v[24:27], v[196:199], v[164:167], v[24:27]
	v_mfma_f32_16x16x32_bf16 v[16:19], v[218:221], v[164:167], v[16:19]
	v_mfma_f32_16x16x32_bf16 v[8:11], v[196:199], v[172:175], v[8:11]
	v_mfma_f32_16x16x32_bf16 v[0:3], v[218:221], v[172:175], v[0:3]
	s_barrier
; #define PG8_STAGE(bufoff, gbase, voff) do { _Pragma("unroll") for (int _i = 0; _i < 2; ++_i) \
;         __builtin_amdgcn_global_load_lds((const unsigned*)((const char*)(gbase) + (voff)[_i]), (LAS unsigned*)(lds + (bufoff) + ldsw + _i * 8192), 16, 0, 0); } while (0)
; #define PG8_LDA(dst, b, h) do { _Pragma("unroll") for (int m = 0; m < 4; ++m) _Pragma("unroll") for (int k = 0; k < 2; ++k) dst[m][k] = *(const LAS bf16x8*)(lds + PG8_SA(b, h) + aoff + m * 2048 + k * 1024); } while (0)
; template <class Prog>
; __device__ __forceinline__ void gemm_phase(LAS unsigned char* lds, const int K, const Prog& S) {
;     ...
;         for (int t = 0; t < nt; t += 2) {
;             const bool last = (t == nt - 2);
;             const char* a1 = cA + (size_t)(t + 1) * kstep;
;             const char* a2 = last ? nA : cA + (size_t)(t + 2) * kstep; const char* b2 = last ? nB : cB + (size_t)(t + 2) * kstep;
;             const char* a3 = a2 + kstep; const char* b3 = b2 + kstep;
;             PG8_LDB(B0, 0, 0); PG8_SCHED; PG8_LDA(At, 0, 0); PG8_STAGE(PG8_SA(1, 1), a1 + hstep, voffA);
;             PG8_WAIT_L(8); PG8_BAR; PG8_WAIT_L(0); PG8_MMA(0, 0, At, B0); PG8_BAR; PG8_SCHED;
;             PG8_LDB(B1, 0, 1); PG8_STAGE(PG8_SB(0, 0), b2, voffB);
;             PG8_BAR; PG8_WAIT_L(0); PG8_MMA(0, 1, At, B1); PG8_BAR;
;             PG8_LDA(At, 0, 1); PG8_STAGE(PG8_SA(0, 0), a2, voffA);
;             PG8_BAR; PG8_WAIT_L(0); PG8_MMA(1, 0, At, B0); PG8_BAR; PG8_SCHED;
;             PG8_STAGE(PG8_SB(0, 1), b2 + hstep, voffB);
;             PG8_WAIT_V(6); PG8_BAR; PG8_MMA(1, 1, At, B1); PG8_BAR;
;             PG8_LDB(B0, 1, 0); PG8_SCHED; PG8_LDA(At, 1, 0); PG8_STAGE(PG8_SA(0, 1), a2 + hstep, voffA);
;             PG8_WAIT_L(8); PG8_BAR; PG8_WAIT_L(0); PG8_MMA(0, 0, At, B0); PG8_BAR; PG8_SCHED;
;             PG8_LDB(B1, 1, 1); PG8_STAGE(PG8_SB(1, 0), b3, voffB);
;             PG8_BAR; PG8_WAIT_L(0); PG8_MMA(0, 1, At, B1); PG8_BAR;
;             PG8_LDA(At, 1, 1); PG8_STAGE(PG8_SA(1, 0), a3, voffA);
;             PG8_BAR; PG8_WAIT_L(0); PG8_MMA(1, 0, At, B0); PG8_BAR; PG8_SCHED;
;             PG8_STAGE(PG8_SB(1, 1), b3 + hstep, voffB);
;             PG8_WAIT_V(6); PG8_BAR; PG8_MMA(1, 1, At, B1); PG8_BAR;
;     ...
;         if (!has_next) break;
;         cur = nxt; cA = nA; cB = nB; ++ui;
;     }
;     PG8_WAIT_V(0);
;     if (wr == 0) PG8_BAR;
;     PG8_BAR;
	s_add_u32 s98, s46, 0x80000
	s_addc_u32 s99, s47, 0
	ds_read_b128 v[128:131], v244 offset:32768
	ds_read_b128 v[132:135], v244 offset:33792
	ds_read_b128 v[136:139], v244 offset:34816
	ds_read_b128 v[140:143], v244 offset:35840
	s_mov_b32 m0, s92
	ds_read_b128 v[188:191], v244 offset:49152
	ds_read_b128 v[196:199], v244 offset:50176
	ds_read_b128 v[200:203], v244 offset:51200
	ds_read_b128 v[218:221], v244 offset:52224
	global_load_lds_dwordx4 v176, s[46:47]
	s_add_i32 m0, s92, 0x2000
	ds_read_b128 v[144:147], v216 offset:32768
	ds_read_b128 v[148:151], v216 offset:33792
	ds_read_b128 v[152:155], v216 offset:34816
	ds_read_b128 v[156:159], v216 offset:35840
	global_load_lds_dwordx4 v178, s[46:47]
	s_add_i32 m0, s92, 0x4000
	ds_read_b128 v[160:163], v216 offset:36864
	ds_read_b128 v[164:167], v216 offset:37888
	ds_read_b128 v[168:171], v216 offset:38912
	global_load_lds_dwordx4 v176, s[98:99]
	s_add_i32 m0, s92, 0x6000
	ds_read_b128 v[172:175], v216 offset:39936
	global_load_lds_dwordx4 v178, s[98:99]
	s_waitcnt lgkmcnt(0)
	s_barrier
	v_mfma_f32_16x16x32_bf16 v[124:127], v[128:131], v[144:147], v[124:127]
	v_mfma_f32_16x16x32_bf16 v[116:119], v[136:139], v[144:147], v[116:119]
	v_mfma_f32_16x16x32_bf16 v[108:111], v[128:131], v[152:155], v[108:111]
	v_mfma_f32_16x16x32_bf16 v[100:103], v[136:139], v[152:155], v[100:103]
	v_mfma_f32_16x16x32_bf16 v[92:95], v[128:131], v[160:163], v[92:95]
	v_mfma_f32_16x16x32_bf16 v[84:87], v[136:139], v[160:163], v[84:87]
	v_mfma_f32_16x16x32_bf16 v[76:79], v[128:131], v[168:171], v[76:79]
	v_mfma_f32_16x16x32_bf16 v[68:71], v[136:139], v[168:171], v[68:71]
	v_mfma_f32_16x16x32_bf16 v[124:127], v[132:135], v[148:151], v[124:127]
	v_mfma_f32_16x16x32_bf16 v[116:119], v[140:143], v[148:151], v[116:119]
	v_mfma_f32_16x16x32_bf16 v[108:111], v[132:135], v[156:159], v[108:111]
	v_mfma_f32_16x16x32_bf16 v[100:103], v[140:143], v[156:159], v[100:103]
	v_mfma_f32_16x16x32_bf16 v[92:95], v[132:135], v[164:167], v[92:95]
	v_mfma_f32_16x16x32_bf16 v[84:87], v[140:143], v[164:167], v[84:87]
	v_mfma_f32_16x16x32_bf16 v[76:79], v[132:135], v[172:175], v[76:79]
	v_mfma_f32_16x16x32_bf16 v[68:71], v[140:143], v[172:175], v[68:71]
	v_mfma_f32_16x16x32_bf16 v[120:123], v[188:191], v[144:147], v[120:123]
	v_mfma_f32_16x16x32_bf16 v[112:115], v[200:203], v[144:147], v[112:115]
	v_mfma_f32_16x16x32_bf16 v[104:107], v[188:191], v[152:155], v[104:107]
	v_mfma_f32_16x16x32_bf16 v[96:99], v[200:203], v[152:155], v[96:99]
	v_mfma_f32_16x16x32_bf16 v[88:91], v[188:191], v[160:163], v[88:91]
	v_mfma_f32_16x16x32_bf16 v[80:83], v[200:203], v[160:163], v[80:83]
	v_mfma_f32_16x16x32_bf16 v[72:75], v[188:191], v[168:171], v[72:75]
	v_mfma_f32_16x16x32_bf16 v[64:67], v[200:203], v[168:171], v[64:67]
	v_mfma_f32_16x16x32_bf16 v[120:123], v[196:199], v[148:151], v[120:123]
	v_mfma_f32_16x16x32_bf16 v[112:115], v[218:221], v[148:151], v[112:115]
	v_mfma_f32_16x16x32_bf16 v[104:107], v[196:199], v[156:159], v[104:107]
	v_mfma_f32_16x16x32_bf16 v[96:99], v[218:221], v[156:159], v[96:99]
	v_mfma_f32_16x16x32_bf16 v[88:91], v[196:199], v[164:167], v[88:91]
	v_mfma_f32_16x16x32_bf16 v[80:83], v[218:221], v[164:167], v[80:83]
	v_mfma_f32_16x16x32_bf16 v[72:75], v[196:199], v[172:175], v[72:75]
	v_mfma_f32_16x16x32_bf16 v[64:67], v[218:221], v[172:175], v[64:67]
	s_barrier
	s_add_u32 s98, s44, 0x80
	s_addc_u32 s99, s45, 0
	s_add_i32 m0, s92, 0x18000
	ds_read_b128 v[144:147], v216 offset:49152
	ds_read_b128 v[148:151], v216 offset:50176
	global_load_lds_dwordx4 v192, s[98:99]
	s_add_i32 m0, s92, 0x1a000
	ds_read_b128 v[152:155], v216 offset:51200
	ds_read_b128 v[156:159], v216 offset:52224
	global_load_lds_dwordx4 v180, s[98:99]
	s_add_i32 m0, s92, 0x1c000
	s_add_u32 s76, s44, 0x80080
	s_addc_u32 s77, s45, 0
	ds_read_b128 v[160:163], v216 offset:53248
	ds_read_b128 v[164:167], v216 offset:54272
	global_load_lds_dwordx4 v192, s[76:77]
	s_add_i32 m0, s92, 0x1e000
	ds_read_b128 v[168:171], v216 offset:55296
	ds_read_b128 v[172:175], v216 offset:56320
	global_load_lds_dwordx4 v180, s[76:77]
	s_waitcnt vmcnt(4) lgkmcnt(0)
	s_barrier
	v_mfma_f32_16x16x32_bf16 v[60:63], v[128:131], v[144:147], v[60:63]
	v_mfma_f32_16x16x32_bf16 v[52:55], v[136:139], v[144:147], v[52:55]
	v_mfma_f32_16x16x32_bf16 v[44:47], v[128:131], v[152:155], v[44:47]
	v_mfma_f32_16x16x32_bf16 v[36:39], v[136:139], v[152:155], v[36:39]
	v_mfma_f32_16x16x32_bf16 v[28:31], v[128:131], v[160:163], v[28:31]
	v_mfma_f32_16x16x32_bf16 v[20:23], v[136:139], v[160:163], v[20:23]
	v_mfma_f32_16x16x32_bf16 v[12:15], v[128:131], v[168:171], v[12:15]
	v_mfma_f32_16x16x32_bf16 v[4:7], v[136:139], v[168:171], v[4:7]
	v_mfma_f32_16x16x32_bf16 v[60:63], v[132:135], v[148:151], v[60:63]
	v_mfma_f32_16x16x32_bf16 v[52:55], v[140:143], v[148:151], v[52:55]
	v_mfma_f32_16x16x32_bf16 v[44:47], v[132:135], v[156:159], v[44:47]
	v_mfma_f32_16x16x32_bf16 v[36:39], v[140:143], v[156:159], v[36:39]
	v_mfma_f32_16x16x32_bf16 v[28:31], v[132:135], v[164:167], v[28:31]
	v_mfma_f32_16x16x32_bf16 v[20:23], v[140:143], v[164:167], v[20:23]
	v_mfma_f32_16x16x32_bf16 v[12:15], v[132:135], v[172:175], v[12:15]
	v_mfma_f32_16x16x32_bf16 v[4:7], v[140:143], v[172:175], v[4:7]
	v_mfma_f32_16x16x32_bf16 v[56:59], v[188:191], v[144:147], v[56:59]
	v_mfma_f32_16x16x32_bf16 v[48:51], v[200:203], v[144:147], v[48:51]
	v_mfma_f32_16x16x32_bf16 v[40:43], v[188:191], v[152:155], v[40:43]
	v_mfma_f32_16x16x32_bf16 v[32:35], v[200:203], v[152:155], v[32:35]
	v_mfma_f32_16x16x32_bf16 v[24:27], v[188:191], v[160:163], v[24:27]
	v_mfma_f32_16x16x32_bf16 v[16:19], v[200:203], v[160:163], v[16:19]
	v_mfma_f32_16x16x32_bf16 v[8:11], v[188:191], v[168:171], v[8:11]
	v_mfma_f32_16x16x32_bf16 v[0:3], v[200:203], v[168:171], v[0:3]
	v_mfma_f32_16x16x32_bf16 v[56:59], v[196:199], v[148:151], v[56:59]
	v_mfma_f32_16x16x32_bf16 v[48:51], v[218:221], v[148:151], v[48:51]
	v_mfma_f32_16x16x32_bf16 v[40:43], v[196:199], v[156:159], v[40:43]
	v_mfma_f32_16x16x32_bf16 v[32:35], v[218:221], v[156:159], v[32:35]
	v_mfma_f32_16x16x32_bf16 v[24:27], v[196:199], v[164:167], v[24:27]
	v_mfma_f32_16x16x32_bf16 v[16:19], v[218:221], v[164:167], v[16:19]
	v_mfma_f32_16x16x32_bf16 v[8:11], v[196:199], v[172:175], v[8:11]
	v_mfma_f32_16x16x32_bf16 v[0:3], v[218:221], v[172:175], v[0:3]
	s_add_i32 s69, s69, 2
	s_add_u32 s40, s40, 0x100
	s_addc_u32 s41, s41, 0
	s_add_u32 s9, s9, 0x100
	s_addc_u32 s15, s15, 0
	s_cmp_gt_u32 s69, 29
	s_barrier
	s_cbranch_scc0 .LBB0_101
	s_cmpk_gt_u32 s85, 0xff
	s_cbranch_scc1 .Lrs_ip_b
	s_barrier

; #define PG8_STAGE(bufoff, gbase, voff) do { _Pragma("unroll") for (int _i = 0; _i < 2; ++_i) \
;         __builtin_amdgcn_global_load_lds((const unsigned*)((const char*)(gbase) + (voff)[_i]), (LAS unsigned*)(lds + (bufoff) + ldsw + _i * 8192), 16, 0, 0); } while (0)
; #define PG8_LDA(dst, b, h) do { _Pragma("unroll") for (int m = 0; m < 4; ++m) _Pragma("unroll") for (int k = 0; k < 2; ++k) dst[m][k] = *(const LAS bf16x8*)(lds + PG8_SA(b, h) + aoff + m * 2048 + k * 1024); } while (0)
; #define PG8_LDB(dst, b, h) do { _Pragma("unroll") for (int n = 0; n < 2; ++n) _Pragma("unroll") for (int k = 0; k < 2; ++k) dst[n][k] = *(const LAS bf16x8*)(lds + PG8_SB(b, h) + boff + n * 2048 + k * 1024); } while (0)
; #define PG8_MMA(ai, bj, At, Bt) do { __builtin_amdgcn_s_setprio(1); _Pragma("unroll") for (int m = 0; m < 4; ++m) _Pragma("unroll") for (int n = 0; n < 2; ++n) _Pragma("unroll") for (int k = 0; k < 2; ++k) \
;         acc[ai][bj][m][n] = __builtin_amdgcn_mfma_f32_16x16x32_bf16(Bt[n][k], At[m][k], acc[ai][bj][m][n], 0, 0, 0); __builtin_amdgcn_s_setprio(0); } while (0)
; #define PG8_WAIT_V(n) asm volatile("s_waitcnt vmcnt(" #n ")" ::: "memory")
; #define PG8_WAIT_L(n) asm volatile("s_waitcnt lgkmcnt(" #n ")" ::: "memory")
; #define PG8_BAR __builtin_amdgcn_s_barrier()
; template <class Prog>
; __device__ __forceinline__ void gemm_phase(LAS unsigned char* lds, const int K, const Prog& S) {
;     ...
;         for (int t = 0; t < nt; t += 2) {
;             const bool last = (t == nt - 2);
;             const char* a1 = cA + (size_t)(t + 1) * kstep;
;             const char* a2 = last ? nA : cA + (size_t)(t + 2) * kstep; const char* b2 = last ? nB : cB + (size_t)(t + 2) * kstep;
;             const char* a3 = a2 + kstep; const char* b3 = b2 + kstep;
;             PG8_LDB(B0, 0, 0); PG8_SCHED; PG8_LDA(At, 0, 0); PG8_STAGE(PG8_SA(1, 1), a1 + hstep, voffA);
;             PG8_WAIT_L(8); PG8_BAR; PG8_WAIT_L(0); PG8_MMA(0, 0, At, B0); PG8_BAR; PG8_SCHED;
;             PG8_LDB(B1, 0, 1); PG8_STAGE(PG8_SB(0, 0), b2, voffB);
;             PG8_BAR; PG8_WAIT_L(0); PG8_MMA(0, 1, At, B1); PG8_BAR;
;             PG8_LDA(At, 0, 1); PG8_STAGE(PG8_SA(0, 0), a2, voffA);
;             PG8_BAR; PG8_WAIT_L(0); PG8_MMA(1, 0, At, B0); PG8_BAR; PG8_SCHED;
;             PG8_STAGE(PG8_SB(0, 1), b2 + hstep, voffB);
;             PG8_WAIT_V(6); PG8_BAR; PG8_MMA(1, 1, At, B1); PG8_BAR;
.LBB0_400:
	s_add_u32 s46, s44, 0xfffc0080
	s_addc_u32 s47, s45, -1
	s_cmp_eq_u32 s55, 12
	s_cselect_b32 s53, s7, s47
	s_cselect_b32 s52, s6, s46
	s_cselect_b32 s47, s9, s43
	s_cselect_b32 s46, s8, s41
	s_add_u32 s84, s44, 0xfffc0000
	s_addc_u32 s85, s45, -1
	ds_read_b128 v[128:131], v206
	ds_read_b128 v[132:135], v206 offset:1024
	ds_read_b128 v[136:139], v206 offset:2048
	ds_read_b128 v[140:143], v206 offset:3072
	s_add_i32 m0, s74, 0x8000
	ds_read_b128 v[176:179], v206 offset:16384
	ds_read_b128 v[180:183], v206 offset:17408
	ds_read_b128 v[184:187], v206 offset:18432
	ds_read_b128 v[188:191], v206 offset:19456
	global_load_lds_dwordx4 v202, s[84:85]
	s_add_i32 m0, s74, 0xa000
	ds_read_b128 v[144:147], v247
	ds_read_b128 v[148:151], v247 offset:1024
	ds_read_b128 v[152:155], v247 offset:2048
	ds_read_b128 v[156:159], v247 offset:3072
	global_load_lds_dwordx4 v204, s[84:85]
	s_add_i32 m0, s74, 0xc000
	ds_read_b128 v[160:163], v247 offset:4096
	ds_read_b128 v[164:167], v247 offset:5120
	ds_read_b128 v[168:171], v247 offset:6144
	global_load_lds_dwordx4 v202, s[44:45]
	s_add_i32 m0, s74, 0xe000
	ds_read_b128 v[172:175], v247 offset:7168
	global_load_lds_dwordx4 v204, s[44:45]
	s_waitcnt lgkmcnt(0)
	s_barrier
	v_mfma_f32_16x16x32_bf16 v[124:127], v[128:131], v[144:147], v[124:127]
	v_mfma_f32_16x16x32_bf16 v[120:123], v[136:139], v[144:147], v[120:123]
	v_mfma_f32_16x16x32_bf16 v[116:119], v[128:131], v[152:155], v[116:119]
	v_mfma_f32_16x16x32_bf16 v[112:115], v[136:139], v[152:155], v[112:115]
	v_mfma_f32_16x16x32_bf16 v[108:111], v[128:131], v[160:163], v[108:111]
	v_mfma_f32_16x16x32_bf16 v[104:107], v[136:139], v[160:163], v[104:107]
	v_mfma_f32_16x16x32_bf16 v[100:103], v[128:131], v[168:171], v[100:103]
	v_mfma_f32_16x16x32_bf16 v[96:99], v[136:139], v[168:171], v[96:99]
	v_mfma_f32_16x16x32_bf16 v[124:127], v[132:135], v[148:151], v[124:127]
	v_mfma_f32_16x16x32_bf16 v[120:123], v[140:143], v[148:151], v[120:123]
	v_mfma_f32_16x16x32_bf16 v[116:119], v[132:135], v[156:159], v[116:119]
	v_mfma_f32_16x16x32_bf16 v[112:115], v[140:143], v[156:159], v[112:115]
	v_mfma_f32_16x16x32_bf16 v[108:111], v[132:135], v[164:167], v[108:111]
	v_mfma_f32_16x16x32_bf16 v[104:107], v[140:143], v[164:167], v[104:107]
	v_mfma_f32_16x16x32_bf16 v[100:103], v[132:135], v[172:175], v[100:103]
	v_mfma_f32_16x16x32_bf16 v[96:99], v[140:143], v[172:175], v[96:99]
	v_mfma_f32_16x16x32_bf16 v[92:95], v[176:179], v[144:147], v[92:95]
	v_mfma_f32_16x16x32_bf16 v[88:91], v[184:187], v[144:147], v[88:91]
	v_mfma_f32_16x16x32_bf16 v[84:87], v[176:179], v[152:155], v[84:87]
	v_mfma_f32_16x16x32_bf16 v[80:83], v[184:187], v[152:155], v[80:83]
	v_mfma_f32_16x16x32_bf16 v[76:79], v[176:179], v[160:163], v[76:79]
	v_mfma_f32_16x16x32_bf16 v[72:75], v[184:187], v[160:163], v[72:75]
	v_mfma_f32_16x16x32_bf16 v[68:71], v[176:179], v[168:171], v[68:71]
	v_mfma_f32_16x16x32_bf16 v[64:67], v[184:187], v[168:171], v[64:67]
	v_mfma_f32_16x16x32_bf16 v[92:95], v[180:183], v[148:151], v[92:95]
	v_mfma_f32_16x16x32_bf16 v[88:91], v[188:191], v[148:151], v[88:91]
	v_mfma_f32_16x16x32_bf16 v[84:87], v[180:183], v[156:159], v[84:87]
	v_mfma_f32_16x16x32_bf16 v[80:83], v[188:191], v[156:159], v[80:83]
	v_mfma_f32_16x16x32_bf16 v[76:79], v[180:183], v[164:167], v[76:79]
	v_mfma_f32_16x16x32_bf16 v[72:75], v[188:191], v[164:167], v[72:75]
	v_mfma_f32_16x16x32_bf16 v[68:71], v[180:183], v[172:175], v[68:71]
	v_mfma_f32_16x16x32_bf16 v[64:67], v[188:191], v[172:175], v[64:67]
	s_barrier
	s_add_i32 m0, s74, 0x10000
	ds_read_b128 v[144:147], v247 offset:16384
	ds_read_b128 v[148:151], v247 offset:17408
	global_load_lds_dwordx4 v192, s[46:47]
	s_add_i32 m0, s74, 0x12000
	ds_read_b128 v[152:155], v247 offset:18432
	ds_read_b128 v[156:159], v247 offset:19456
	global_load_lds_dwordx4 v200, s[46:47]
	s_add_i32 m0, s74, 0x14000
	s_add_u32 s84, s46, 0x40000
	s_addc_u32 s85, s47, 0
	ds_read_b128 v[160:163], v247 offset:20480
	ds_read_b128 v[164:167], v247 offset:21504
	global_load_lds_dwordx4 v192, s[84:85]
	s_add_i32 m0, s74, 0x16000
	ds_read_b128 v[168:171], v247 offset:22528
	ds_read_b128 v[172:175], v247 offset:23552
	global_load_lds_dwordx4 v200, s[84:85]
	s_waitcnt vmcnt(4) lgkmcnt(0)
	s_barrier
	v_mfma_f32_16x16x32_bf16 v[60:63], v[128:131], v[144:147], v[60:63]
	v_mfma_f32_16x16x32_bf16 v[56:59], v[136:139], v[144:147], v[56:59]
	v_mfma_f32_16x16x32_bf16 v[52:55], v[128:131], v[152:155], v[52:55]
	v_mfma_f32_16x16x32_bf16 v[48:51], v[136:139], v[152:155], v[48:51]
	v_mfma_f32_16x16x32_bf16 v[44:47], v[128:131], v[160:163], v[44:47]
	v_mfma_f32_16x16x32_bf16 v[40:43], v[136:139], v[160:163], v[40:43]
	v_mfma_f32_16x16x32_bf16 v[36:39], v[128:131], v[168:171], v[36:39]
	v_mfma_f32_16x16x32_bf16 v[32:35], v[136:139], v[168:171], v[32:35]
	v_mfma_f32_16x16x32_bf16 v[60:63], v[132:135], v[148:151], v[60:63]
	v_mfma_f32_16x16x32_bf16 v[56:59], v[140:143], v[148:151], v[56:59]
	v_mfma_f32_16x16x32_bf16 v[52:55], v[132:135], v[156:159], v[52:55]
	v_mfma_f32_16x16x32_bf16 v[48:51], v[140:143], v[156:159], v[48:51]
	v_mfma_f32_16x16x32_bf16 v[44:47], v[132:135], v[164:167], v[44:47]
	v_mfma_f32_16x16x32_bf16 v[40:43], v[140:143], v[164:167], v[40:43]
	v_mfma_f32_16x16x32_bf16 v[36:39], v[132:135], v[172:175], v[36:39]
	v_mfma_f32_16x16x32_bf16 v[32:35], v[140:143], v[172:175], v[32:35]
	v_mfma_f32_16x16x32_bf16 v[28:31], v[176:179], v[144:147], v[28:31]
	v_mfma_f32_16x16x32_bf16 v[24:27], v[184:187], v[144:147], v[24:27]
	v_mfma_f32_16x16x32_bf16 v[20:23], v[176:179], v[152:155], v[20:23]
	v_mfma_f32_16x16x32_bf16 v[16:19], v[184:187], v[152:155], v[16:19]
	v_mfma_f32_16x16x32_bf16 v[12:15], v[176:179], v[160:163], v[12:15]
	v_mfma_f32_16x16x32_bf16 v[8:11], v[184:187], v[160:163], v[8:11]
	v_mfma_f32_16x16x32_bf16 v[4:7], v[176:179], v[168:171], v[4:7]
	v_mfma_f32_16x16x32_bf16 v[0:3], v[184:187], v[168:171], v[0:3]
	v_mfma_f32_16x16x32_bf16 v[28:31], v[180:183], v[148:151], v[28:31]
	v_mfma_f32_16x16x32_bf16 v[24:27], v[188:191], v[148:151], v[24:27]
	v_mfma_f32_16x16x32_bf16 v[20:23], v[180:183], v[156:159], v[20:23]
	v_mfma_f32_16x16x32_bf16 v[16:19], v[188:191], v[156:159], v[16:19]
	v_mfma_f32_16x16x32_bf16 v[12:15], v[180:183], v[164:167], v[12:15]
	v_mfma_f32_16x16x32_bf16 v[8:11], v[188:191], v[164:167], v[8:11]
	v_mfma_f32_16x16x32_bf16 v[4:7], v[180:183], v[172:175], v[4:7]
	v_mfma_f32_16x16x32_bf16 v[0:3], v[188:191], v[172:175], v[0:3]
	s_barrier
; #define PG8_STAGE(bufoff, gbase, voff) do { _Pragma("unroll") for (int _i = 0; _i < 2; ++_i) \
;         __builtin_amdgcn_global_load_lds((const unsigned*)((const char*)(gbase) + (voff)[_i]), (LAS unsigned*)(lds + (bufoff) + ldsw + _i * 8192), 16, 0, 0); } while (0)
; #define PG8_LDA(dst, b, h) do { _Pragma("unroll") for (int m = 0; m < 4; ++m) _Pragma("unroll") for (int k = 0; k < 2; ++k) dst[m][k] = *(const LAS bf16x8*)(lds + PG8_SA(b, h) + aoff + m * 2048 + k * 1024); } while (0)
; template <class Prog>
; __device__ __forceinline__ void gemm_phase(LAS unsigned char* lds, const int K, const Prog& S) {
;     ...
;         for (int t = 0; t < nt; t += 2) {
;             const bool last = (t == nt - 2);
;             const char* a1 = cA + (size_t)(t + 1) * kstep;
;             const char* a2 = last ? nA : cA + (size_t)(t + 2) * kstep; const char* b2 = last ? nB : cB + (size_t)(t + 2) * kstep;
;             const char* a3 = a2 + kstep; const char* b3 = b2 + kstep;
;             PG8_LDB(B0, 0, 0); PG8_SCHED; PG8_LDA(At, 0, 0); PG8_STAGE(PG8_SA(1, 1), a1 + hstep, voffA);
;             PG8_WAIT_L(8); PG8_BAR; PG8_WAIT_L(0); PG8_MMA(0, 0, At, B0); PG8_BAR; PG8_SCHED;
;             PG8_LDB(B1, 0, 1); PG8_STAGE(PG8_SB(0, 0), b2, voffB);
;             PG8_BAR; PG8_WAIT_L(0); PG8_MMA(0, 1, At, B1); PG8_BAR;
;             PG8_LDA(At, 0, 1); PG8_STAGE(PG8_SA(0, 0), a2, voffA);
;             PG8_BAR; PG8_WAIT_L(0); PG8_MMA(1, 0, At, B0); PG8_BAR; PG8_SCHED;
;             PG8_STAGE(PG8_SB(0, 1), b2 + hstep, voffB);
;             PG8_WAIT_V(6); PG8_BAR; PG8_MMA(1, 1, At, B1); PG8_BAR;
;             PG8_LDB(B0, 1, 0); PG8_SCHED; PG8_LDA(At, 1, 0); PG8_STAGE(PG8_SA(0, 1), a2 + hstep, voffA);
;             PG8_WAIT_L(8); PG8_BAR; PG8_WAIT_L(0); PG8_MMA(0, 0, At, B0); PG8_BAR; PG8_SCHED;
;             PG8_LDB(B1, 1, 1); PG8_STAGE(PG8_SB(1, 0), b3, voffB);
;             PG8_BAR; PG8_WAIT_L(0); PG8_MMA(0, 1, At, B1); PG8_BAR;
;             PG8_LDA(At, 1, 1); PG8_STAGE(PG8_SA(1, 0), a3, voffA);
;             PG8_BAR; PG8_WAIT_L(0); PG8_MMA(1, 0, At, B0); PG8_BAR; PG8_SCHED;
;             PG8_STAGE(PG8_SB(1, 1), b3 + hstep, voffB);
;             PG8_WAIT_V(6); PG8_BAR; PG8_MMA(1, 1, At, B1); PG8_BAR;
;     ...
;         if (!has_next) break;
;         cur = nxt; cA = nA; cB = nB; ++ui;
;     }
;     PG8_WAIT_V(0);
;     if (wr == 0) PG8_BAR;
;     PG8_BAR;
	s_add_u32 s98, s52, 0x40000
	s_addc_u32 s99, s53, 0
	ds_read_b128 v[128:131], v206 offset:32768
	ds_read_b128 v[132:135], v206 offset:33792
	ds_read_b128 v[136:139], v206 offset:34816
	ds_read_b128 v[140:143], v206 offset:35840
	s_mov_b32 m0, s74
	ds_read_b128 v[176:179], v206 offset:49152
	ds_read_b128 v[180:183], v206 offset:50176
	ds_read_b128 v[184:187], v206 offset:51200
	ds_read_b128 v[188:191], v206 offset:52224
	global_load_lds_dwordx4 v196, s[52:53]
	s_add_i32 m0, s74, 0x2000
	ds_read_b128 v[144:147], v247 offset:32768
	ds_read_b128 v[148:151], v247 offset:33792
	ds_read_b128 v[152:155], v247 offset:34816
	ds_read_b128 v[156:159], v247 offset:35840
	global_load_lds_dwordx4 v198, s[52:53]
	s_add_i32 m0, s74, 0x4000
	ds_read_b128 v[160:163], v247 offset:36864
	ds_read_b128 v[164:167], v247 offset:37888
	ds_read_b128 v[168:171], v247 offset:38912
	global_load_lds_dwordx4 v196, s[98:99]
	s_add_i32 m0, s74, 0x6000
	ds_read_b128 v[172:175], v247 offset:39936
	global_load_lds_dwordx4 v198, s[98:99]
	s_waitcnt lgkmcnt(0)
	s_barrier
	v_mfma_f32_16x16x32_bf16 v[124:127], v[128:131], v[144:147], v[124:127]
	v_mfma_f32_16x16x32_bf16 v[120:123], v[136:139], v[144:147], v[120:123]
	v_mfma_f32_16x16x32_bf16 v[116:119], v[128:131], v[152:155], v[116:119]
	v_mfma_f32_16x16x32_bf16 v[112:115], v[136:139], v[152:155], v[112:115]
	v_mfma_f32_16x16x32_bf16 v[108:111], v[128:131], v[160:163], v[108:111]
	v_mfma_f32_16x16x32_bf16 v[104:107], v[136:139], v[160:163], v[104:107]
	v_mfma_f32_16x16x32_bf16 v[100:103], v[128:131], v[168:171], v[100:103]
	v_mfma_f32_16x16x32_bf16 v[96:99], v[136:139], v[168:171], v[96:99]
	v_mfma_f32_16x16x32_bf16 v[124:127], v[132:135], v[148:151], v[124:127]
	v_mfma_f32_16x16x32_bf16 v[120:123], v[140:143], v[148:151], v[120:123]
	v_mfma_f32_16x16x32_bf16 v[116:119], v[132:135], v[156:159], v[116:119]
	v_mfma_f32_16x16x32_bf16 v[112:115], v[140:143], v[156:159], v[112:115]
	v_mfma_f32_16x16x32_bf16 v[108:111], v[132:135], v[164:167], v[108:111]
	v_mfma_f32_16x16x32_bf16 v[104:107], v[140:143], v[164:167], v[104:107]
	v_mfma_f32_16x16x32_bf16 v[100:103], v[132:135], v[172:175], v[100:103]
	v_mfma_f32_16x16x32_bf16 v[96:99], v[140:143], v[172:175], v[96:99]
	v_mfma_f32_16x16x32_bf16 v[92:95], v[176:179], v[144:147], v[92:95]
	v_mfma_f32_16x16x32_bf16 v[88:91], v[184:187], v[144:147], v[88:91]
	v_mfma_f32_16x16x32_bf16 v[84:87], v[176:179], v[152:155], v[84:87]
	v_mfma_f32_16x16x32_bf16 v[80:83], v[184:187], v[152:155], v[80:83]
	v_mfma_f32_16x16x32_bf16 v[76:79], v[176:179], v[160:163], v[76:79]
	v_mfma_f32_16x16x32_bf16 v[72:75], v[184:187], v[160:163], v[72:75]
	v_mfma_f32_16x16x32_bf16 v[68:71], v[176:179], v[168:171], v[68:71]
	v_mfma_f32_16x16x32_bf16 v[64:67], v[184:187], v[168:171], v[64:67]
	v_mfma_f32_16x16x32_bf16 v[92:95], v[180:183], v[148:151], v[92:95]
	v_mfma_f32_16x16x32_bf16 v[88:91], v[188:191], v[148:151], v[88:91]
	v_mfma_f32_16x16x32_bf16 v[84:87], v[180:183], v[156:159], v[84:87]
	v_mfma_f32_16x16x32_bf16 v[80:83], v[188:191], v[156:159], v[80:83]
	v_mfma_f32_16x16x32_bf16 v[76:79], v[180:183], v[164:167], v[76:79]
	v_mfma_f32_16x16x32_bf16 v[72:75], v[188:191], v[164:167], v[72:75]
	v_mfma_f32_16x16x32_bf16 v[68:71], v[180:183], v[172:175], v[68:71]
	v_mfma_f32_16x16x32_bf16 v[64:67], v[188:191], v[172:175], v[64:67]
	s_barrier
	s_add_u32 s98, s46, 0x80
	s_addc_u32 s99, s47, 0
	s_add_i32 m0, s74, 0x18000
	ds_read_b128 v[144:147], v247 offset:49152
	ds_read_b128 v[148:151], v247 offset:50176
	global_load_lds_dwordx4 v192, s[98:99]
	s_add_i32 m0, s74, 0x1a000
	ds_read_b128 v[152:155], v247 offset:51200
	ds_read_b128 v[156:159], v247 offset:52224
	global_load_lds_dwordx4 v200, s[98:99]
	s_add_i32 m0, s74, 0x1c000
	s_add_u32 s84, s46, 0x40080
	s_addc_u32 s85, s47, 0
	ds_read_b128 v[160:163], v247 offset:53248
	ds_read_b128 v[164:167], v247 offset:54272
	global_load_lds_dwordx4 v192, s[84:85]
	s_add_i32 m0, s74, 0x1e000
	ds_read_b128 v[168:171], v247 offset:55296
	ds_read_b128 v[172:175], v247 offset:56320
	global_load_lds_dwordx4 v200, s[84:85]
	s_waitcnt vmcnt(4) lgkmcnt(0)
	s_barrier
	v_mfma_f32_16x16x32_bf16 v[60:63], v[128:131], v[144:147], v[60:63]
	v_mfma_f32_16x16x32_bf16 v[56:59], v[136:139], v[144:147], v[56:59]
	v_mfma_f32_16x16x32_bf16 v[52:55], v[128:131], v[152:155], v[52:55]
	v_mfma_f32_16x16x32_bf16 v[48:51], v[136:139], v[152:155], v[48:51]
	v_mfma_f32_16x16x32_bf16 v[44:47], v[128:131], v[160:163], v[44:47]
	v_mfma_f32_16x16x32_bf16 v[40:43], v[136:139], v[160:163], v[40:43]
	v_mfma_f32_16x16x32_bf16 v[36:39], v[128:131], v[168:171], v[36:39]
	v_mfma_f32_16x16x32_bf16 v[32:35], v[136:139], v[168:171], v[32:35]
	v_mfma_f32_16x16x32_bf16 v[60:63], v[132:135], v[148:151], v[60:63]
	v_mfma_f32_16x16x32_bf16 v[56:59], v[140:143], v[148:151], v[56:59]
	v_mfma_f32_16x16x32_bf16 v[52:55], v[132:135], v[156:159], v[52:55]
	v_mfma_f32_16x16x32_bf16 v[48:51], v[140:143], v[156:159], v[48:51]
	v_mfma_f32_16x16x32_bf16 v[44:47], v[132:135], v[164:167], v[44:47]
	v_mfma_f32_16x16x32_bf16 v[40:43], v[140:143], v[164:167], v[40:43]
	v_mfma_f32_16x16x32_bf16 v[36:39], v[132:135], v[172:175], v[36:39]
	v_mfma_f32_16x16x32_bf16 v[32:35], v[140:143], v[172:175], v[32:35]
	v_mfma_f32_16x16x32_bf16 v[28:31], v[176:179], v[144:147], v[28:31]
	v_mfma_f32_16x16x32_bf16 v[24:27], v[184:187], v[144:147], v[24:27]
	v_mfma_f32_16x16x32_bf16 v[20:23], v[176:179], v[152:155], v[20:23]
	v_mfma_f32_16x16x32_bf16 v[16:19], v[184:187], v[152:155], v[16:19]
	v_mfma_f32_16x16x32_bf16 v[12:15], v[176:179], v[160:163], v[12:15]
	v_mfma_f32_16x16x32_bf16 v[8:11], v[184:187], v[160:163], v[8:11]
	v_mfma_f32_16x16x32_bf16 v[4:7], v[176:179], v[168:171], v[4:7]
	v_mfma_f32_16x16x32_bf16 v[0:3], v[184:187], v[168:171], v[0:3]
	v_mfma_f32_16x16x32_bf16 v[28:31], v[180:183], v[148:151], v[28:31]
	v_mfma_f32_16x16x32_bf16 v[24:27], v[188:191], v[148:151], v[24:27]
	v_mfma_f32_16x16x32_bf16 v[20:23], v[180:183], v[156:159], v[20:23]
	v_mfma_f32_16x16x32_bf16 v[16:19], v[188:191], v[156:159], v[16:19]
	v_mfma_f32_16x16x32_bf16 v[12:15], v[180:183], v[164:167], v[12:15]
	v_mfma_f32_16x16x32_bf16 v[8:11], v[188:191], v[164:167], v[8:11]
	v_mfma_f32_16x16x32_bf16 v[4:7], v[180:183], v[172:175], v[4:7]
	v_mfma_f32_16x16x32_bf16 v[0:3], v[188:191], v[172:175], v[0:3]
	s_add_i32 s55, s55, 2
	s_add_u32 s44, s44, 0x100
	s_addc_u32 s45, s45, 0
	s_add_u32 s41, s41, 0x100
	s_addc_u32 s43, s43, 0
	s_cmp_gt_u32 s55, 13
	s_barrier
	s_cbranch_scc0 .LBB0_400
	s_cmpk_gt_u32 s62, 0xff
	s_cbranch_scc1 .Lrs_mg_b
	s_barrier

; #define PG8_STAGE(bufoff, gbase, voff) do { _Pragma("unroll") for (int _i = 0; _i < 2; ++_i) \
;         __builtin_amdgcn_global_load_lds((const unsigned*)((const char*)(gbase) + (voff)[_i]), (LAS unsigned*)(lds + (bufoff) + ldsw + _i * 8192), 16, 0, 0); } while (0)
; #define PG8_LDA(dst, b, h) do { _Pragma("unroll") for (int m = 0; m < 4; ++m) _Pragma("unroll") for (int k = 0; k < 2; ++k) dst[m][k] = *(const LAS bf16x8*)(lds + PG8_SA(b, h) + aoff + m * 2048 + k * 1024); } while (0)
; #define PG8_LDB(dst, b, h) do { _Pragma("unroll") for (int n = 0; n < 2; ++n) _Pragma("unroll") for (int k = 0; k < 2; ++k) dst[n][k] = *(const LAS bf16x8*)(lds + PG8_SB(b, h) + boff + n * 2048 + k * 1024); } while (0)
; #define PG8_MMA(ai, bj, At, Bt) do { __builtin_amdgcn_s_setprio(1); _Pragma("unroll") for (int m = 0; m < 4; ++m) _Pragma("unroll") for (int n = 0; n < 2; ++n) _Pragma("unroll") for (int k = 0; k < 2; ++k) \
;         acc[ai][bj][m][n] = __builtin_amdgcn_mfma_f32_16x16x32_bf16(Bt[n][k], At[m][k], acc[ai][bj][m][n], 0, 0, 0); __builtin_amdgcn_s_setprio(0); } while (0)
; #define PG8_WAIT_V(n) asm volatile("s_waitcnt vmcnt(" #n ")" ::: "memory")
; #define PG8_WAIT_L(n) asm volatile("s_waitcnt lgkmcnt(" #n ")" ::: "memory")
; #define PG8_BAR __builtin_amdgcn_s_barrier()
; template <class Prog>
; __device__ __forceinline__ void gemm_phase(LAS unsigned char* lds, const int K, const Prog& S) {
;     ...
;         for (int t = 0; t < nt; t += 2) {
;             const bool last = (t == nt - 2);
;             const char* a1 = cA + (size_t)(t + 1) * kstep;
;             const char* a2 = last ? nA : cA + (size_t)(t + 2) * kstep; const char* b2 = last ? nB : cB + (size_t)(t + 2) * kstep;
;             const char* a3 = a2 + kstep; const char* b3 = b2 + kstep;
;             PG8_LDB(B0, 0, 0); PG8_SCHED; PG8_LDA(At, 0, 0); PG8_STAGE(PG8_SA(1, 1), a1 + hstep, voffA);
;             PG8_WAIT_L(8); PG8_BAR; PG8_WAIT_L(0); PG8_MMA(0, 0, At, B0); PG8_BAR; PG8_SCHED;
;             PG8_LDB(B1, 0, 1); PG8_STAGE(PG8_SB(0, 0), b2, voffB);
;             PG8_BAR; PG8_WAIT_L(0); PG8_MMA(0, 1, At, B1); PG8_BAR;
;             PG8_LDA(At, 0, 1); PG8_STAGE(PG8_SA(0, 0), a2, voffA);
;             PG8_BAR; PG8_WAIT_L(0); PG8_MMA(1, 0, At, B0); PG8_BAR; PG8_SCHED;
;             PG8_STAGE(PG8_SB(0, 1), b2 + hstep, voffB);
;             PG8_WAIT_V(6); PG8_BAR; PG8_MMA(1, 1, At, B1); PG8_BAR;
.LBB0_571:
	s_add_u32 s52, s46, 0xfff80080
	s_addc_u32 s53, s47, -1
	s_cmp_eq_u32 s54, 28
	s_cselect_b32 s93, s7, s53
	s_cselect_b32 s92, s6, s52
	s_cselect_b32 s53, s45, s43
	s_cselect_b32 s52, s44, s41
	s_add_u32 vcc_lo, s46, 0xfff80000
	s_addc_u32 vcc_hi, s47, -1
	ds_read_b128 v[128:131], v202
	ds_read_b128 v[132:135], v202 offset:1024
	ds_read_b128 v[136:139], v202 offset:2048
	ds_read_b128 v[140:143], v202 offset:3072
	s_add_i32 m0, s75, 0x8000
	ds_read_b128 v[176:179], v202 offset:16384
	ds_read_b128 v[180:183], v202 offset:17408
	ds_read_b128 v[184:187], v202 offset:18432
	ds_read_b128 v[198:201], v202 offset:19456
	global_load_lds_dwordx4 v190, vcc
	s_add_i32 m0, s75, 0xa000
	ds_read_b128 v[144:147], v217
	ds_read_b128 v[148:151], v217 offset:1024
	ds_read_b128 v[152:155], v217 offset:2048
	ds_read_b128 v[156:159], v217 offset:3072
	global_load_lds_dwordx4 v196, vcc
	s_add_i32 m0, s75, 0xc000
	ds_read_b128 v[160:163], v217 offset:4096
	ds_read_b128 v[164:167], v217 offset:5120
	ds_read_b128 v[168:171], v217 offset:6144
	global_load_lds_dwordx4 v190, s[46:47]
	s_add_i32 m0, s75, 0xe000
	ds_read_b128 v[172:175], v217 offset:7168
	global_load_lds_dwordx4 v196, s[46:47]
	s_waitcnt lgkmcnt(0)
	s_barrier
	v_mfma_f32_16x16x32_bf16 v[124:127], v[128:131], v[144:147], v[124:127]
	v_mfma_f32_16x16x32_bf16 v[120:123], v[136:139], v[144:147], v[120:123]
	v_mfma_f32_16x16x32_bf16 v[108:111], v[128:131], v[152:155], v[108:111]
	v_mfma_f32_16x16x32_bf16 v[104:107], v[136:139], v[152:155], v[104:107]
	v_mfma_f32_16x16x32_bf16 v[92:95], v[128:131], v[160:163], v[92:95]
	v_mfma_f32_16x16x32_bf16 v[88:91], v[136:139], v[160:163], v[88:91]
	v_mfma_f32_16x16x32_bf16 v[76:79], v[128:131], v[168:171], v[76:79]
	v_mfma_f32_16x16x32_bf16 v[72:75], v[136:139], v[168:171], v[72:75]
	v_mfma_f32_16x16x32_bf16 v[124:127], v[132:135], v[148:151], v[124:127]
	v_mfma_f32_16x16x32_bf16 v[120:123], v[140:143], v[148:151], v[120:123]
	v_mfma_f32_16x16x32_bf16 v[108:111], v[132:135], v[156:159], v[108:111]
	v_mfma_f32_16x16x32_bf16 v[104:107], v[140:143], v[156:159], v[104:107]
	v_mfma_f32_16x16x32_bf16 v[92:95], v[132:135], v[164:167], v[92:95]
	v_mfma_f32_16x16x32_bf16 v[88:91], v[140:143], v[164:167], v[88:91]
	v_mfma_f32_16x16x32_bf16 v[76:79], v[132:135], v[172:175], v[76:79]
	v_mfma_f32_16x16x32_bf16 v[72:75], v[140:143], v[172:175], v[72:75]
	v_mfma_f32_16x16x32_bf16 v[116:119], v[176:179], v[144:147], v[116:119]
	v_mfma_f32_16x16x32_bf16 v[112:115], v[184:187], v[144:147], v[112:115]
	v_mfma_f32_16x16x32_bf16 v[100:103], v[176:179], v[152:155], v[100:103]
	v_mfma_f32_16x16x32_bf16 v[96:99], v[184:187], v[152:155], v[96:99]
	v_mfma_f32_16x16x32_bf16 v[84:87], v[176:179], v[160:163], v[84:87]
	v_mfma_f32_16x16x32_bf16 v[80:83], v[184:187], v[160:163], v[80:83]
	v_mfma_f32_16x16x32_bf16 v[68:71], v[176:179], v[168:171], v[68:71]
	v_mfma_f32_16x16x32_bf16 v[64:67], v[184:187], v[168:171], v[64:67]
	v_mfma_f32_16x16x32_bf16 v[116:119], v[180:183], v[148:151], v[116:119]
	v_mfma_f32_16x16x32_bf16 v[112:115], v[198:201], v[148:151], v[112:115]
	v_mfma_f32_16x16x32_bf16 v[100:103], v[180:183], v[156:159], v[100:103]
	v_mfma_f32_16x16x32_bf16 v[96:99], v[198:201], v[156:159], v[96:99]
	v_mfma_f32_16x16x32_bf16 v[84:87], v[180:183], v[164:167], v[84:87]
	v_mfma_f32_16x16x32_bf16 v[80:83], v[198:201], v[164:167], v[80:83]
	v_mfma_f32_16x16x32_bf16 v[68:71], v[180:183], v[172:175], v[68:71]
	v_mfma_f32_16x16x32_bf16 v[64:67], v[198:201], v[172:175], v[64:67]
	s_barrier
	s_add_i32 m0, s75, 0x10000
	ds_read_b128 v[144:147], v217 offset:16384
	ds_read_b128 v[148:151], v217 offset:17408
	global_load_lds_dwordx4 v192, s[52:53]
	s_add_i32 m0, s75, 0x12000
	ds_read_b128 v[152:155], v217 offset:18432
	ds_read_b128 v[156:159], v217 offset:19456
	global_load_lds_dwordx4 v188, s[52:53]
	s_add_i32 m0, s75, 0x14000
	s_add_u32 vcc_lo, s52, 0x80000
	s_addc_u32 vcc_hi, s53, 0
	ds_read_b128 v[160:163], v217 offset:20480
	ds_read_b128 v[164:167], v217 offset:21504
	global_load_lds_dwordx4 v192, vcc
	s_add_i32 m0, s75, 0x16000
	ds_read_b128 v[168:171], v217 offset:22528
	ds_read_b128 v[172:175], v217 offset:23552
	global_load_lds_dwordx4 v188, vcc
	s_waitcnt vmcnt(4) lgkmcnt(0)
	s_barrier
	v_mfma_f32_16x16x32_bf16 v[60:63], v[128:131], v[144:147], v[60:63]
	v_mfma_f32_16x16x32_bf16 v[56:59], v[136:139], v[144:147], v[56:59]
	v_mfma_f32_16x16x32_bf16 v[44:47], v[128:131], v[152:155], v[44:47]
	v_mfma_f32_16x16x32_bf16 v[40:43], v[136:139], v[152:155], v[40:43]
	v_mfma_f32_16x16x32_bf16 v[28:31], v[128:131], v[160:163], v[28:31]
	v_mfma_f32_16x16x32_bf16 v[24:27], v[136:139], v[160:163], v[24:27]
	v_mfma_f32_16x16x32_bf16 v[12:15], v[128:131], v[168:171], v[12:15]
	v_mfma_f32_16x16x32_bf16 v[8:11], v[136:139], v[168:171], v[8:11]
	v_mfma_f32_16x16x32_bf16 v[60:63], v[132:135], v[148:151], v[60:63]
	v_mfma_f32_16x16x32_bf16 v[56:59], v[140:143], v[148:151], v[56:59]
	v_mfma_f32_16x16x32_bf16 v[44:47], v[132:135], v[156:159], v[44:47]
	v_mfma_f32_16x16x32_bf16 v[40:43], v[140:143], v[156:159], v[40:43]
	v_mfma_f32_16x16x32_bf16 v[28:31], v[132:135], v[164:167], v[28:31]
	v_mfma_f32_16x16x32_bf16 v[24:27], v[140:143], v[164:167], v[24:27]
	v_mfma_f32_16x16x32_bf16 v[12:15], v[132:135], v[172:175], v[12:15]
	v_mfma_f32_16x16x32_bf16 v[8:11], v[140:143], v[172:175], v[8:11]
	v_mfma_f32_16x16x32_bf16 v[52:55], v[176:179], v[144:147], v[52:55]
	v_mfma_f32_16x16x32_bf16 v[48:51], v[184:187], v[144:147], v[48:51]
	v_mfma_f32_16x16x32_bf16 v[36:39], v[176:179], v[152:155], v[36:39]
	v_mfma_f32_16x16x32_bf16 v[32:35], v[184:187], v[152:155], v[32:35]
	v_mfma_f32_16x16x32_bf16 v[20:23], v[176:179], v[160:163], v[20:23]
	v_mfma_f32_16x16x32_bf16 v[16:19], v[184:187], v[160:163], v[16:19]
	v_mfma_f32_16x16x32_bf16 v[4:7], v[176:179], v[168:171], v[4:7]
	v_mfma_f32_16x16x32_bf16 v[0:3], v[184:187], v[168:171], v[0:3]
	v_mfma_f32_16x16x32_bf16 v[52:55], v[180:183], v[148:151], v[52:55]
	v_mfma_f32_16x16x32_bf16 v[48:51], v[198:201], v[148:151], v[48:51]
	v_mfma_f32_16x16x32_bf16 v[36:39], v[180:183], v[156:159], v[36:39]
	v_mfma_f32_16x16x32_bf16 v[32:35], v[198:201], v[156:159], v[32:35]
	v_mfma_f32_16x16x32_bf16 v[20:23], v[180:183], v[164:167], v[20:23]
	v_mfma_f32_16x16x32_bf16 v[16:19], v[198:201], v[164:167], v[16:19]
	v_mfma_f32_16x16x32_bf16 v[4:7], v[180:183], v[172:175], v[4:7]
	v_mfma_f32_16x16x32_bf16 v[0:3], v[198:201], v[172:175], v[0:3]
	s_barrier
; #define PG8_STAGE(bufoff, gbase, voff) do { _Pragma("unroll") for (int _i = 0; _i < 2; ++_i) \
;         __builtin_amdgcn_global_load_lds((const unsigned*)((const char*)(gbase) + (voff)[_i]), (LAS unsigned*)(lds + (bufoff) + ldsw + _i * 8192), 16, 0, 0); } while (0)
; #define PG8_LDA(dst, b, h) do { _Pragma("unroll") for (int m = 0; m < 4; ++m) _Pragma("unroll") for (int k = 0; k < 2; ++k) dst[m][k] = *(const LAS bf16x8*)(lds + PG8_SA(b, h) + aoff + m * 2048 + k * 1024); } while (0)
; template <class Prog>
; __device__ __forceinline__ void gemm_phase(LAS unsigned char* lds, const int K, const Prog& S) {
;     ...
;         for (int t = 0; t < nt; t += 2) {
;             const bool last = (t == nt - 2);
;             const char* a1 = cA + (size_t)(t + 1) * kstep;
;             const char* a2 = last ? nA : cA + (size_t)(t + 2) * kstep; const char* b2 = last ? nB : cB + (size_t)(t + 2) * kstep;
;             const char* a3 = a2 + kstep; const char* b3 = b2 + kstep;
;             PG8_LDB(B0, 0, 0); PG8_SCHED; PG8_LDA(At, 0, 0); PG8_STAGE(PG8_SA(1, 1), a1 + hstep, voffA);
;             PG8_WAIT_L(8); PG8_BAR; PG8_WAIT_L(0); PG8_MMA(0, 0, At, B0); PG8_BAR; PG8_SCHED;
;             PG8_LDB(B1, 0, 1); PG8_STAGE(PG8_SB(0, 0), b2, voffB);
;             PG8_BAR; PG8_WAIT_L(0); PG8_MMA(0, 1, At, B1); PG8_BAR;
;             PG8_LDA(At, 0, 1); PG8_STAGE(PG8_SA(0, 0), a2, voffA);
;             PG8_BAR; PG8_WAIT_L(0); PG8_MMA(1, 0, At, B0); PG8_BAR; PG8_SCHED;
;             PG8_STAGE(PG8_SB(0, 1), b2 + hstep, voffB);
;             PG8_WAIT_V(6); PG8_BAR; PG8_MMA(1, 1, At, B1); PG8_BAR;
;             PG8_LDB(B0, 1, 0); PG8_SCHED; PG8_LDA(At, 1, 0); PG8_STAGE(PG8_SA(0, 1), a2 + hstep, voffA);
;             PG8_WAIT_L(8); PG8_BAR; PG8_WAIT_L(0); PG8_MMA(0, 0, At, B0); PG8_BAR; PG8_SCHED;
;             PG8_LDB(B1, 1, 1); PG8_STAGE(PG8_SB(1, 0), b3, voffB);
;             PG8_BAR; PG8_WAIT_L(0); PG8_MMA(0, 1, At, B1); PG8_BAR;
;             PG8_LDA(At, 1, 1); PG8_STAGE(PG8_SA(1, 0), a3, voffA);
;             PG8_BAR; PG8_WAIT_L(0); PG8_MMA(1, 0, At, B0); PG8_BAR; PG8_SCHED;
;             PG8_STAGE(PG8_SB(1, 1), b3 + hstep, voffB);
;             PG8_WAIT_V(6); PG8_BAR; PG8_MMA(1, 1, At, B1); PG8_BAR;
;     ...
;         if (!has_next) break;
;         cur = nxt; cA = nA; cB = nB; ++ui;
;     }
;     PG8_WAIT_V(0);
;     if (wr == 0) PG8_BAR;
;     PG8_BAR;
	s_add_u32 s98, s92, 0x80000
	s_addc_u32 s99, s93, 0
	ds_read_b128 v[128:131], v202 offset:32768
	ds_read_b128 v[132:135], v202 offset:33792
	ds_read_b128 v[136:139], v202 offset:34816
	ds_read_b128 v[140:143], v202 offset:35840
	s_mov_b32 m0, s75
	ds_read_b128 v[176:179], v202 offset:49152
	ds_read_b128 v[180:183], v202 offset:50176
	ds_read_b128 v[184:187], v202 offset:51200
	ds_read_b128 v[198:201], v202 offset:52224
	global_load_lds_dwordx4 v192, s[92:93]
	s_add_i32 m0, s75, 0x2000
	ds_read_b128 v[144:147], v217 offset:32768
	ds_read_b128 v[148:151], v217 offset:33792
	ds_read_b128 v[152:155], v217 offset:34816
	ds_read_b128 v[156:159], v217 offset:35840
	global_load_lds_dwordx4 v188, s[92:93]
	s_add_i32 m0, s75, 0x4000
	ds_read_b128 v[160:163], v217 offset:36864
	ds_read_b128 v[164:167], v217 offset:37888
	ds_read_b128 v[168:171], v217 offset:38912
	global_load_lds_dwordx4 v192, s[98:99]
	s_add_i32 m0, s75, 0x6000
	ds_read_b128 v[172:175], v217 offset:39936
	global_load_lds_dwordx4 v188, s[98:99]
	s_waitcnt lgkmcnt(0)
	s_barrier
	v_mfma_f32_16x16x32_bf16 v[124:127], v[128:131], v[144:147], v[124:127]
	v_mfma_f32_16x16x32_bf16 v[120:123], v[136:139], v[144:147], v[120:123]
	v_mfma_f32_16x16x32_bf16 v[108:111], v[128:131], v[152:155], v[108:111]
	v_mfma_f32_16x16x32_bf16 v[104:107], v[136:139], v[152:155], v[104:107]
	v_mfma_f32_16x16x32_bf16 v[92:95], v[128:131], v[160:163], v[92:95]
	v_mfma_f32_16x16x32_bf16 v[88:91], v[136:139], v[160:163], v[88:91]
	v_mfma_f32_16x16x32_bf16 v[76:79], v[128:131], v[168:171], v[76:79]
	v_mfma_f32_16x16x32_bf16 v[72:75], v[136:139], v[168:171], v[72:75]
	v_mfma_f32_16x16x32_bf16 v[124:127], v[132:135], v[148:151], v[124:127]
	v_mfma_f32_16x16x32_bf16 v[120:123], v[140:143], v[148:151], v[120:123]
	v_mfma_f32_16x16x32_bf16 v[108:111], v[132:135], v[156:159], v[108:111]
	v_mfma_f32_16x16x32_bf16 v[104:107], v[140:143], v[156:159], v[104:107]
	v_mfma_f32_16x16x32_bf16 v[92:95], v[132:135], v[164:167], v[92:95]
	v_mfma_f32_16x16x32_bf16 v[88:91], v[140:143], v[164:167], v[88:91]
	v_mfma_f32_16x16x32_bf16 v[76:79], v[132:135], v[172:175], v[76:79]
	v_mfma_f32_16x16x32_bf16 v[72:75], v[140:143], v[172:175], v[72:75]
	v_mfma_f32_16x16x32_bf16 v[116:119], v[176:179], v[144:147], v[116:119]
	v_mfma_f32_16x16x32_bf16 v[112:115], v[184:187], v[144:147], v[112:115]
	v_mfma_f32_16x16x32_bf16 v[100:103], v[176:179], v[152:155], v[100:103]
	v_mfma_f32_16x16x32_bf16 v[96:99], v[184:187], v[152:155], v[96:99]
	v_mfma_f32_16x16x32_bf16 v[84:87], v[176:179], v[160:163], v[84:87]
	v_mfma_f32_16x16x32_bf16 v[80:83], v[184:187], v[160:163], v[80:83]
	v_mfma_f32_16x16x32_bf16 v[68:71], v[176:179], v[168:171], v[68:71]
	v_mfma_f32_16x16x32_bf16 v[64:67], v[184:187], v[168:171], v[64:67]
	v_mfma_f32_16x16x32_bf16 v[116:119], v[180:183], v[148:151], v[116:119]
	v_mfma_f32_16x16x32_bf16 v[112:115], v[198:201], v[148:151], v[112:115]
	v_mfma_f32_16x16x32_bf16 v[100:103], v[180:183], v[156:159], v[100:103]
	v_mfma_f32_16x16x32_bf16 v[96:99], v[198:201], v[156:159], v[96:99]
	v_mfma_f32_16x16x32_bf16 v[84:87], v[180:183], v[164:167], v[84:87]
	v_mfma_f32_16x16x32_bf16 v[80:83], v[198:201], v[164:167], v[80:83]
	v_mfma_f32_16x16x32_bf16 v[68:71], v[180:183], v[172:175], v[68:71]
	v_mfma_f32_16x16x32_bf16 v[64:67], v[198:201], v[172:175], v[64:67]
	s_barrier
	s_add_u32 s98, s52, 0x80
	s_addc_u32 s99, s53, 0
	s_add_i32 m0, s75, 0x18000
	ds_read_b128 v[144:147], v217 offset:49152
	ds_read_b128 v[148:151], v217 offset:50176
	global_load_lds_dwordx4 v192, s[98:99]
	s_add_i32 m0, s75, 0x1a000
	ds_read_b128 v[152:155], v217 offset:51200
	ds_read_b128 v[156:159], v217 offset:52224
	global_load_lds_dwordx4 v188, s[98:99]
	s_add_i32 m0, s75, 0x1c000
	s_add_u32 vcc_lo, s52, 0x80080
	s_addc_u32 vcc_hi, s53, 0
	ds_read_b128 v[160:163], v217 offset:53248
	ds_read_b128 v[164:167], v217 offset:54272
	global_load_lds_dwordx4 v192, vcc
	s_add_i32 m0, s75, 0x1e000
	ds_read_b128 v[168:171], v217 offset:55296
	ds_read_b128 v[172:175], v217 offset:56320
	global_load_lds_dwordx4 v188, vcc
	s_waitcnt vmcnt(4) lgkmcnt(0)
	s_barrier
	v_mfma_f32_16x16x32_bf16 v[60:63], v[128:131], v[144:147], v[60:63]
	v_mfma_f32_16x16x32_bf16 v[56:59], v[136:139], v[144:147], v[56:59]
	v_mfma_f32_16x16x32_bf16 v[44:47], v[128:131], v[152:155], v[44:47]
	v_mfma_f32_16x16x32_bf16 v[40:43], v[136:139], v[152:155], v[40:43]
	v_mfma_f32_16x16x32_bf16 v[28:31], v[128:131], v[160:163], v[28:31]
	v_mfma_f32_16x16x32_bf16 v[24:27], v[136:139], v[160:163], v[24:27]
	v_mfma_f32_16x16x32_bf16 v[12:15], v[128:131], v[168:171], v[12:15]
	v_mfma_f32_16x16x32_bf16 v[8:11], v[136:139], v[168:171], v[8:11]
	v_mfma_f32_16x16x32_bf16 v[60:63], v[132:135], v[148:151], v[60:63]
	v_mfma_f32_16x16x32_bf16 v[56:59], v[140:143], v[148:151], v[56:59]
	v_mfma_f32_16x16x32_bf16 v[44:47], v[132:135], v[156:159], v[44:47]
	v_mfma_f32_16x16x32_bf16 v[40:43], v[140:143], v[156:159], v[40:43]
	v_mfma_f32_16x16x32_bf16 v[28:31], v[132:135], v[164:167], v[28:31]
	v_mfma_f32_16x16x32_bf16 v[24:27], v[140:143], v[164:167], v[24:27]
	v_mfma_f32_16x16x32_bf16 v[12:15], v[132:135], v[172:175], v[12:15]
	v_mfma_f32_16x16x32_bf16 v[8:11], v[140:143], v[172:175], v[8:11]
	v_mfma_f32_16x16x32_bf16 v[52:55], v[176:179], v[144:147], v[52:55]
	v_mfma_f32_16x16x32_bf16 v[48:51], v[184:187], v[144:147], v[48:51]
	v_mfma_f32_16x16x32_bf16 v[36:39], v[176:179], v[152:155], v[36:39]
	v_mfma_f32_16x16x32_bf16 v[32:35], v[184:187], v[152:155], v[32:35]
	v_mfma_f32_16x16x32_bf16 v[20:23], v[176:179], v[160:163], v[20:23]
	v_mfma_f32_16x16x32_bf16 v[16:19], v[184:187], v[160:163], v[16:19]
	v_mfma_f32_16x16x32_bf16 v[4:7], v[176:179], v[168:171], v[4:7]
	v_mfma_f32_16x16x32_bf16 v[0:3], v[184:187], v[168:171], v[0:3]
	v_mfma_f32_16x16x32_bf16 v[52:55], v[180:183], v[148:151], v[52:55]
	v_mfma_f32_16x16x32_bf16 v[48:51], v[198:201], v[148:151], v[48:51]
	v_mfma_f32_16x16x32_bf16 v[36:39], v[180:183], v[156:159], v[36:39]
	v_mfma_f32_16x16x32_bf16 v[32:35], v[198:201], v[156:159], v[32:35]
	v_mfma_f32_16x16x32_bf16 v[20:23], v[180:183], v[164:167], v[20:23]
	v_mfma_f32_16x16x32_bf16 v[16:19], v[198:201], v[164:167], v[16:19]
	v_mfma_f32_16x16x32_bf16 v[4:7], v[180:183], v[172:175], v[4:7]
	v_mfma_f32_16x16x32_bf16 v[0:3], v[198:201], v[172:175], v[0:3]
	s_add_i32 s54, s54, 2
	s_add_u32 s46, s46, 0x100
	s_addc_u32 s47, s47, 0
	s_add_u32 s41, s41, 0x100
	s_addc_u32 s43, s43, 0
	s_cmp_gt_u32 s54, 29
	s_barrier
	s_cbranch_scc0 .LBB0_571
	s_cmpk_gt_u32 s72, 0xff
	s_cbranch_scc1 .Lrs_op_b
	s_barrier
